# MLA fast path: softmax exp/sum fully interleaved into QK^T and PV MFMA shadows, V-fragment reads issued ahead of the PV chain (bit-identical)
# speedup vs baseline: 1.0095x; 1.0095x over previous
; DI unsigned pack2(float a, float b) { bf2_t v = __builtin_convertvector((f32x2){a, b}, bf2_t); return __builtin_bit_cast(unsigned, v); }
; #define MFMA32(a, b, c) __builtin_amdgcn_mfma_f32_32x32x16_bf16((a), (b), (c), 0, 0, 0)
; template <int DQK, int MODE, bool QN, bool KN> ...
;     ...
;       } else if (fixed_shift) {
;         float ps = 0.f;
; #pragma unroll
;         for (int kb = 0; kb < 2; ++kb)
; #pragma unroll
;           for (int i = 0; i < 16; ++i) { const float pv = __builtin_amdgcn_exp2f(sacc[kb][i]); sacc[kb][i] = pv; ps += pv; }
;         l_run += ps;
;     ...
; #pragma unroll
;       for (int kb = 0; kb < 2; ++kb)
; #pragma unroll
;         for (int s2 = 0; s2 < 2; ++s2) {
;           u32x4 pw;
;           pw.x = pack2(sacc[kb][8 * s2 + 0], sacc[kb][8 * s2 + 1]); pw.y = pack2(sacc[kb][8 * s2 + 2], sacc[kb][8 * s2 + 3]);
;           pw.z = pack2(sacc[kb][8 * s2 + 4], sacc[kb][8 * s2 + 5]); pw.w = pack2(sacc[kb][8 * s2 + 6], sacc[kb][8 * s2 + 7]);
;           const bf16x8 pf = __builtin_bit_cast(bf16x8, pw);
; #pragma unroll
;           for (int dvb = 0; dvb < 2; ++dvb) {
;             const char* vb = sV + dvb * VIMG + (kb * 32 + 16 * s2) * 64 + vtr_off;
;             const s16x4 v0 = tr_read(vb), v1 = tr_read(vb + 8 * 64);
;             const bf16x8 vf = __builtin_shufflevector(v0, v1, 0, 1, 2, 3, 4, 5, 6, 7);
;             o[dvb] = MFMA32(vf, pf, o[dvb]);
;           }
;         }
.Lmfp_0:
	s_waitcnt lgkmcnt(5)
	v_mfma_f32_32x32x16_bf16 v[64:79], v[112:115], v[160:163], v[16:31]
	s_waitcnt lgkmcnt(4)
	v_mfma_f32_32x32x16_bf16 v[64:79], v[116:119], v[164:167], v[64:79]
	s_nop 7
	v_exp_f32_e32 v112, v80
	v_exp_f32_e32 v113, v81
	v_exp_f32_e32 v114, v82
	v_exp_f32_e32 v115, v83
	v_add_u32_e32 v14, 0x110, v249
	s_waitcnt lgkmcnt(3)
	v_mfma_f32_32x32x16_bf16 v[64:79], v[120:123], v[168:171], v[64:79]
	v_exp_f32_e32 v116, v84
	v_exp_f32_e32 v117, v85
	v_exp_f32_e32 v118, v86
	v_exp_f32_e32 v119, v87
	v_add_f32_e32 v0, 0, v112
	v_add_f32_e32 v0, v113, v0
	v_add_f32_e32 v0, v114, v0
	v_add_f32_e32 v0, v115, v0
	s_waitcnt lgkmcnt(2)
	v_mfma_f32_32x32x16_bf16 v[64:79], v[124:127], v[172:175], v[64:79]
	v_exp_f32_e32 v120, v88
	v_exp_f32_e32 v121, v89
	v_exp_f32_e32 v122, v90
	v_exp_f32_e32 v123, v91
	v_add_f32_e32 v0, v116, v0
	v_add_f32_e32 v0, v117, v0
	v_add_f32_e32 v0, v118, v0
	v_add_f32_e32 v0, v119, v0
	s_waitcnt lgkmcnt(1)
	v_mfma_f32_32x32x16_bf16 v[64:79], v[144:147], v[176:179], v[64:79]
	v_exp_f32_e32 v124, v92
	v_exp_f32_e32 v125, v93
	v_exp_f32_e32 v126, v94
	v_exp_f32_e32 v127, v95
	v_add_f32_e32 v0, v120, v0
	v_add_f32_e32 v0, v121, v0
	v_add_f32_e32 v0, v122, v0
	v_add_f32_e32 v0, v123, v0
	s_waitcnt lgkmcnt(0)
	v_mfma_f32_32x32x16_bf16 v[64:79], v[148:151], v[180:183], v[64:79]
	ds_read_b64_tr_b16 v[32:33], v14 offset:26624
	ds_read_b64_tr_b16 v[34:35], v14 offset:27136
	ds_read_b64_tr_b16 v[36:37], v14 offset:34816
	ds_read_b64_tr_b16 v[38:39], v14 offset:35328
	ds_read_b64_tr_b16 v[40:41], v14 offset:27648
	ds_read_b64_tr_b16 v[42:43], v14 offset:28160
	ds_read_b64_tr_b16 v[44:45], v14 offset:35840
	ds_read_b64_tr_b16 v[46:47], v14 offset:36352
	ds_read_b64_tr_b16 v[48:49], v14 offset:28672
	ds_read_b64_tr_b16 v[50:51], v14 offset:29184
	ds_read_b64_tr_b16 v[52:53], v14 offset:36864
	ds_read_b64_tr_b16 v[54:55], v14 offset:37376
	v_add_f32_e32 v0, v124, v0
	v_add_f32_e32 v0, v125, v0
	v_add_f32_e32 v0, v126, v0
	v_add_f32_e32 v0, v127, v0
	v_cvt_pk_bf16_f32 v80, v112, v113
	v_cvt_pk_bf16_f32 v81, v114, v115
	v_cvt_pk_bf16_f32 v82, v116, v117
	v_cvt_pk_bf16_f32 v83, v118, v119
	v_cvt_pk_bf16_f32 v84, v120, v121
	v_cvt_pk_bf16_f32 v85, v122, v123
	v_cvt_pk_bf16_f32 v86, v124, v125
	v_cvt_pk_bf16_f32 v87, v126, v127
	s_waitcnt lgkmcnt(10)
	s_nop 0
	v_mfma_f32_32x32x16_bf16 v[96:111], v[32:35], v[80:83], v[96:111]
	v_exp_f32_e32 v144, v64
	v_exp_f32_e32 v145, v65
	v_exp_f32_e32 v146, v66
	v_exp_f32_e32 v147, v67
	s_waitcnt lgkmcnt(8)
	v_mfma_f32_32x32x16_bf16 v[128:143], v[36:39], v[80:83], v[128:143]
	ds_read_b64_tr_b16 v[56:57], v14 offset:29696
	ds_read_b64_tr_b16 v[58:59], v14 offset:30208
	ds_read_b64_tr_b16 v[60:61], v14 offset:37888
	ds_read_b64_tr_b16 v[62:63], v14 offset:38400
	v_exp_f32_e32 v148, v68
	v_exp_f32_e32 v149, v69
	v_exp_f32_e32 v150, v70
	v_exp_f32_e32 v151, v71
	v_add_f32_e32 v0, v144, v0
	v_add_f32_e32 v0, v145, v0
	v_add_f32_e32 v0, v146, v0
	v_add_f32_e32 v0, v147, v0
	s_waitcnt lgkmcnt(10)
	v_mfma_f32_32x32x16_bf16 v[96:111], v[40:43], v[84:87], v[96:111]
	v_exp_f32_e32 v152, v72
	v_exp_f32_e32 v153, v73
	v_exp_f32_e32 v154, v74
	v_exp_f32_e32 v155, v75
	v_add_f32_e32 v0, v148, v0
	v_add_f32_e32 v0, v149, v0
	v_add_f32_e32 v0, v150, v0
	v_add_f32_e32 v0, v151, v0
	s_waitcnt lgkmcnt(8)
	v_mfma_f32_32x32x16_bf16 v[128:143], v[44:47], v[84:87], v[128:143]
	v_exp_f32_e32 v156, v76
	v_exp_f32_e32 v157, v77
	v_exp_f32_e32 v158, v78
	v_exp_f32_e32 v159, v79
	v_add_f32_e32 v0, v152, v0
	v_add_f32_e32 v0, v153, v0
	v_add_f32_e32 v0, v154, v0
	v_add_f32_e32 v0, v155, v0
	v_cvt_pk_bf16_f32 v88, v144, v145
	v_cvt_pk_bf16_f32 v89, v146, v147
	v_cvt_pk_bf16_f32 v90, v148, v149
	v_cvt_pk_bf16_f32 v91, v150, v151
	v_add_f32_e32 v0, v156, v0
	v_add_f32_e32 v0, v157, v0
	v_add_f32_e32 v0, v158, v0
	v_add_f32_e32 v0, v159, v0
	v_cvt_pk_bf16_f32 v92, v152, v153
	v_cvt_pk_bf16_f32 v93, v154, v155
	v_cvt_pk_bf16_f32 v94, v156, v157
	v_cvt_pk_bf16_f32 v95, v158, v159
	v_add_f32_e32 v15, v253, v0
	s_waitcnt lgkmcnt(6)
	s_nop 0
	v_mfma_f32_32x32x16_bf16 v[96:111], v[48:51], v[88:91], v[96:111]
	s_waitcnt lgkmcnt(4)
	v_mfma_f32_32x32x16_bf16 v[128:143], v[52:55], v[88:91], v[128:143]
	s_waitcnt lgkmcnt(2)
	v_mfma_f32_32x32x16_bf16 v[96:111], v[56:59], v[92:95], v[96:111]
	s_waitcnt lgkmcnt(0)
	v_mfma_f32_32x32x16_bf16 v[128:143], v[60:63], v[92:95], v[128:143]
	v_mov_b32_e32 v253, v15
	s_branch .LBB0_1208
; DI unsigned pack2(float a, float b) { bf2_t v = __builtin_convertvector((f32x2){a, b}, bf2_t); return __builtin_bit_cast(unsigned, v); }
; #define MFMA32(a, b, c) __builtin_amdgcn_mfma_f32_32x32x16_bf16((a), (b), (c), 0, 0, 0)
; template <int DQK, int MODE, bool QN, bool KN> ...
;     ...
;       } else if (fixed_shift) {
;         float ps = 0.f;
; #pragma unroll
;         for (int kb = 0; kb < 2; ++kb)
; #pragma unroll
;           for (int i = 0; i < 16; ++i) { const float pv = __builtin_amdgcn_exp2f(sacc[kb][i]); sacc[kb][i] = pv; ps += pv; }
;         l_run += ps;
;     ...
; #pragma unroll
;       for (int kb = 0; kb < 2; ++kb)
; #pragma unroll
;         for (int s2 = 0; s2 < 2; ++s2) {
;           u32x4 pw;
;           pw.x = pack2(sacc[kb][8 * s2 + 0], sacc[kb][8 * s2 + 1]); pw.y = pack2(sacc[kb][8 * s2 + 2], sacc[kb][8 * s2 + 3]);
;           pw.z = pack2(sacc[kb][8 * s2 + 4], sacc[kb][8 * s2 + 5]); pw.w = pack2(sacc[kb][8 * s2 + 6], sacc[kb][8 * s2 + 7]);
;           const bf16x8 pf = __builtin_bit_cast(bf16x8, pw);
; #pragma unroll
;           for (int dvb = 0; dvb < 2; ++dvb) {
;             const char* vb = sV + dvb * VIMG + (kb * 32 + 16 * s2) * 64 + vtr_off;
;             const s16x4 v0 = tr_read(vb), v1 = tr_read(vb + 8 * 64);
;             const bf16x8 vf = __builtin_shufflevector(v0, v1, 0, 1, 2, 3, 4, 5, 6, 7);
;             o[dvb] = MFMA32(vf, pf, o[dvb]);
;           }
;         }
.Lmfp_1:
	s_waitcnt lgkmcnt(5)
	v_mfma_f32_32x32x16_bf16 v[64:79], v[112:115], v[160:163], v[16:31]
	s_waitcnt lgkmcnt(4)
	v_mfma_f32_32x32x16_bf16 v[64:79], v[116:119], v[164:167], v[64:79]
	s_nop 7
	v_exp_f32_e32 v112, v80
	v_exp_f32_e32 v113, v81
	v_exp_f32_e32 v114, v82
	v_exp_f32_e32 v115, v83
	v_add_u32_e32 v14, 0x110, v249
	s_waitcnt lgkmcnt(3)
	v_mfma_f32_32x32x16_bf16 v[64:79], v[120:123], v[168:171], v[64:79]
	v_exp_f32_e32 v116, v84
	v_exp_f32_e32 v117, v85
	v_exp_f32_e32 v118, v86
	v_exp_f32_e32 v119, v87
	v_add_f32_e32 v0, 0, v112
	v_add_f32_e32 v0, v113, v0
	v_add_f32_e32 v0, v114, v0
	v_add_f32_e32 v0, v115, v0
	s_waitcnt lgkmcnt(2)
	v_mfma_f32_32x32x16_bf16 v[64:79], v[124:127], v[172:175], v[64:79]
	v_exp_f32_e32 v120, v88
	v_exp_f32_e32 v121, v89
	v_exp_f32_e32 v122, v90
	v_exp_f32_e32 v123, v91
	v_add_f32_e32 v0, v116, v0
	v_add_f32_e32 v0, v117, v0
	v_add_f32_e32 v0, v118, v0
	v_add_f32_e32 v0, v119, v0
	s_waitcnt lgkmcnt(1)
	v_mfma_f32_32x32x16_bf16 v[64:79], v[144:147], v[176:179], v[64:79]
	v_exp_f32_e32 v124, v92
	v_exp_f32_e32 v125, v93
	v_exp_f32_e32 v126, v94
	v_exp_f32_e32 v127, v95
	v_add_f32_e32 v0, v120, v0
	v_add_f32_e32 v0, v121, v0
	v_add_f32_e32 v0, v122, v0
	v_add_f32_e32 v0, v123, v0
	s_waitcnt lgkmcnt(0)
	v_mfma_f32_32x32x16_bf16 v[64:79], v[148:151], v[180:183], v[64:79]
	ds_read_b64_tr_b16 v[32:33], v14 offset:30720
	ds_read_b64_tr_b16 v[34:35], v14 offset:31232
	ds_read_b64_tr_b16 v[36:37], v14 offset:38912
	ds_read_b64_tr_b16 v[38:39], v14 offset:39424
	ds_read_b64_tr_b16 v[40:41], v14 offset:31744
	ds_read_b64_tr_b16 v[42:43], v14 offset:32256
	ds_read_b64_tr_b16 v[44:45], v14 offset:39936
	ds_read_b64_tr_b16 v[46:47], v14 offset:40448
	ds_read_b64_tr_b16 v[48:49], v14 offset:32768
	ds_read_b64_tr_b16 v[50:51], v14 offset:33280
	ds_read_b64_tr_b16 v[52:53], v14 offset:40960
	ds_read_b64_tr_b16 v[54:55], v14 offset:41472
	v_add_f32_e32 v0, v124, v0
	v_add_f32_e32 v0, v125, v0
	v_add_f32_e32 v0, v126, v0
	v_add_f32_e32 v0, v127, v0
	v_cvt_pk_bf16_f32 v80, v112, v113
	v_cvt_pk_bf16_f32 v81, v114, v115
	v_cvt_pk_bf16_f32 v82, v116, v117
	v_cvt_pk_bf16_f32 v83, v118, v119
	v_cvt_pk_bf16_f32 v84, v120, v121
	v_cvt_pk_bf16_f32 v85, v122, v123
	v_cvt_pk_bf16_f32 v86, v124, v125
	v_cvt_pk_bf16_f32 v87, v126, v127
	s_waitcnt lgkmcnt(10)
	s_nop 0
	v_mfma_f32_32x32x16_bf16 v[96:111], v[32:35], v[80:83], v[96:111]
	v_exp_f32_e32 v144, v64
	v_exp_f32_e32 v145, v65
	v_exp_f32_e32 v146, v66
	v_exp_f32_e32 v147, v67
	s_waitcnt lgkmcnt(8)
	v_mfma_f32_32x32x16_bf16 v[128:143], v[36:39], v[80:83], v[128:143]
	ds_read_b64_tr_b16 v[56:57], v14 offset:33792
	ds_read_b64_tr_b16 v[58:59], v14 offset:34304
	ds_read_b64_tr_b16 v[60:61], v14 offset:41984
	ds_read_b64_tr_b16 v[62:63], v14 offset:42496
	v_exp_f32_e32 v148, v68
	v_exp_f32_e32 v149, v69
	v_exp_f32_e32 v150, v70
	v_exp_f32_e32 v151, v71
	v_add_f32_e32 v0, v144, v0
	v_add_f32_e32 v0, v145, v0
	v_add_f32_e32 v0, v146, v0
	v_add_f32_e32 v0, v147, v0
	s_waitcnt lgkmcnt(10)
	v_mfma_f32_32x32x16_bf16 v[96:111], v[40:43], v[84:87], v[96:111]
	v_exp_f32_e32 v152, v72
	v_exp_f32_e32 v153, v73
	v_exp_f32_e32 v154, v74
	v_exp_f32_e32 v155, v75
	v_add_f32_e32 v0, v148, v0
	v_add_f32_e32 v0, v149, v0
	v_add_f32_e32 v0, v150, v0
	v_add_f32_e32 v0, v151, v0
	s_waitcnt lgkmcnt(8)
	v_mfma_f32_32x32x16_bf16 v[128:143], v[44:47], v[84:87], v[128:143]
	v_exp_f32_e32 v156, v76
	v_exp_f32_e32 v157, v77
	v_exp_f32_e32 v158, v78
	v_exp_f32_e32 v159, v79
	v_add_f32_e32 v0, v152, v0
	v_add_f32_e32 v0, v153, v0
	v_add_f32_e32 v0, v154, v0
	v_add_f32_e32 v0, v155, v0
	v_cvt_pk_bf16_f32 v88, v144, v145
	v_cvt_pk_bf16_f32 v89, v146, v147
	v_cvt_pk_bf16_f32 v90, v148, v149
	v_cvt_pk_bf16_f32 v91, v150, v151
	v_add_f32_e32 v0, v156, v0
	v_add_f32_e32 v0, v157, v0
	v_add_f32_e32 v0, v158, v0
	v_add_f32_e32 v0, v159, v0
	v_cvt_pk_bf16_f32 v92, v152, v153
	v_cvt_pk_bf16_f32 v93, v154, v155
	v_cvt_pk_bf16_f32 v94, v156, v157
	v_cvt_pk_bf16_f32 v95, v158, v159
	v_add_f32_e32 v15, v253, v0
	s_waitcnt lgkmcnt(6)
	s_nop 0
	v_mfma_f32_32x32x16_bf16 v[96:111], v[48:51], v[88:91], v[96:111]
	s_waitcnt lgkmcnt(4)
	v_mfma_f32_32x32x16_bf16 v[128:143], v[52:55], v[88:91], v[128:143]
	s_waitcnt lgkmcnt(2)
	v_mfma_f32_32x32x16_bf16 v[96:111], v[56:59], v[92:95], v[96:111]
	s_waitcnt lgkmcnt(0)
	v_mfma_f32_32x32x16_bf16 v[128:143], v[60:63], v[92:95], v[128:143]
	v_mov_b32_e32 v253, v15
	s_branch .LBB0_1218
; DI unsigned pack2(float a, float b) { bf2_t v = __builtin_convertvector((f32x2){a, b}, bf2_t); return __builtin_bit_cast(unsigned, v); }
; #define MFMA32(a, b, c) __builtin_amdgcn_mfma_f32_32x32x16_bf16((a), (b), (c), 0, 0, 0)
; template <int DQK, int MODE, bool QN, bool KN> ...
;     ...
;       } else if (fixed_shift) {
;         float ps = 0.f;
; #pragma unroll
;         for (int kb = 0; kb < 2; ++kb)
; #pragma unroll
;           for (int i = 0; i < 16; ++i) { const float pv = __builtin_amdgcn_exp2f(sacc[kb][i]); sacc[kb][i] = pv; ps += pv; }
;         l_run += ps;
;     ...
; #pragma unroll
;       for (int kb = 0; kb < 2; ++kb)
; #pragma unroll
;         for (int s2 = 0; s2 < 2; ++s2) {
;           u32x4 pw;
;           pw.x = pack2(sacc[kb][8 * s2 + 0], sacc[kb][8 * s2 + 1]); pw.y = pack2(sacc[kb][8 * s2 + 2], sacc[kb][8 * s2 + 3]);
;           pw.z = pack2(sacc[kb][8 * s2 + 4], sacc[kb][8 * s2 + 5]); pw.w = pack2(sacc[kb][8 * s2 + 6], sacc[kb][8 * s2 + 7]);
;           const bf16x8 pf = __builtin_bit_cast(bf16x8, pw);
; #pragma unroll
;           for (int dvb = 0; dvb < 2; ++dvb) {
;             const char* vb = sV + dvb * VIMG + (kb * 32 + 16 * s2) * 64 + vtr_off;
;             const s16x4 v0 = tr_read(vb), v1 = tr_read(vb + 8 * 64);
;             const bf16x8 vf = __builtin_shufflevector(v0, v1, 0, 1, 2, 3, 4, 5, 6, 7);
;             o[dvb] = MFMA32(vf, pf, o[dvb]);
;           }
;         }
.Lmfp_2:
	s_waitcnt lgkmcnt(5)
	v_mfma_f32_32x32x16_bf16 v[64:79], v[112:115], v[160:163], v[16:31]
	s_waitcnt lgkmcnt(4)
	v_mfma_f32_32x32x16_bf16 v[64:79], v[116:119], v[164:167], v[64:79]
	s_nop 7
	v_exp_f32_e32 v112, v80
	v_exp_f32_e32 v113, v81
	v_exp_f32_e32 v114, v82
	v_exp_f32_e32 v115, v83
	v_add_u32_e32 v14, 0x11110, v249
	s_waitcnt lgkmcnt(3)
	v_mfma_f32_32x32x16_bf16 v[64:79], v[120:123], v[168:171], v[64:79]
	v_exp_f32_e32 v116, v84
	v_exp_f32_e32 v117, v85
	v_exp_f32_e32 v118, v86
	v_exp_f32_e32 v119, v87
	v_add_f32_e32 v0, 0, v112
	v_add_f32_e32 v0, v113, v0
	v_add_f32_e32 v0, v114, v0
	v_add_f32_e32 v0, v115, v0
	s_waitcnt lgkmcnt(2)
	v_mfma_f32_32x32x16_bf16 v[64:79], v[124:127], v[172:175], v[64:79]
	v_exp_f32_e32 v120, v88
	v_exp_f32_e32 v121, v89
	v_exp_f32_e32 v122, v90
	v_exp_f32_e32 v123, v91
	v_add_f32_e32 v0, v116, v0
	v_add_f32_e32 v0, v117, v0
	v_add_f32_e32 v0, v118, v0
	v_add_f32_e32 v0, v119, v0
	s_waitcnt lgkmcnt(1)
	v_mfma_f32_32x32x16_bf16 v[64:79], v[144:147], v[176:179], v[64:79]
	v_exp_f32_e32 v124, v92
	v_exp_f32_e32 v125, v93
	v_exp_f32_e32 v126, v94
	v_exp_f32_e32 v127, v95
	v_add_f32_e32 v0, v120, v0
	v_add_f32_e32 v0, v121, v0
	v_add_f32_e32 v0, v122, v0
	v_add_f32_e32 v0, v123, v0
	s_waitcnt lgkmcnt(0)
	v_mfma_f32_32x32x16_bf16 v[64:79], v[148:151], v[180:183], v[64:79]
	ds_read_b64_tr_b16 v[32:33], v14 offset:0
	ds_read_b64_tr_b16 v[34:35], v14 offset:512
	ds_read_b64_tr_b16 v[36:37], v14 offset:8192
	ds_read_b64_tr_b16 v[38:39], v14 offset:8704
	ds_read_b64_tr_b16 v[40:41], v14 offset:1024
	ds_read_b64_tr_b16 v[42:43], v14 offset:1536
	ds_read_b64_tr_b16 v[44:45], v14 offset:9216
	ds_read_b64_tr_b16 v[46:47], v14 offset:9728
	ds_read_b64_tr_b16 v[48:49], v14 offset:2048
	ds_read_b64_tr_b16 v[50:51], v14 offset:2560
	ds_read_b64_tr_b16 v[52:53], v14 offset:10240
	ds_read_b64_tr_b16 v[54:55], v14 offset:10752
	v_add_f32_e32 v0, v124, v0
	v_add_f32_e32 v0, v125, v0
	v_add_f32_e32 v0, v126, v0
	v_add_f32_e32 v0, v127, v0
	v_cvt_pk_bf16_f32 v80, v112, v113
	v_cvt_pk_bf16_f32 v81, v114, v115
	v_cvt_pk_bf16_f32 v82, v116, v117
	v_cvt_pk_bf16_f32 v83, v118, v119
	v_cvt_pk_bf16_f32 v84, v120, v121
	v_cvt_pk_bf16_f32 v85, v122, v123
	v_cvt_pk_bf16_f32 v86, v124, v125
	v_cvt_pk_bf16_f32 v87, v126, v127
	s_waitcnt lgkmcnt(10)
	s_nop 0
	v_mfma_f32_32x32x16_bf16 v[96:111], v[32:35], v[80:83], v[96:111]
	v_exp_f32_e32 v144, v64
	v_exp_f32_e32 v145, v65
	v_exp_f32_e32 v146, v66
	v_exp_f32_e32 v147, v67
	s_waitcnt lgkmcnt(8)
	v_mfma_f32_32x32x16_bf16 v[128:143], v[36:39], v[80:83], v[128:143]
	ds_read_b64_tr_b16 v[56:57], v14 offset:3072
	ds_read_b64_tr_b16 v[58:59], v14 offset:3584
	ds_read_b64_tr_b16 v[60:61], v14 offset:11264
	ds_read_b64_tr_b16 v[62:63], v14 offset:11776
	v_exp_f32_e32 v148, v68
	v_exp_f32_e32 v149, v69
	v_exp_f32_e32 v150, v70
	v_exp_f32_e32 v151, v71
	v_add_f32_e32 v0, v144, v0
	v_add_f32_e32 v0, v145, v0
	v_add_f32_e32 v0, v146, v0
	v_add_f32_e32 v0, v147, v0
	s_waitcnt lgkmcnt(10)
	v_mfma_f32_32x32x16_bf16 v[96:111], v[40:43], v[84:87], v[96:111]
	v_exp_f32_e32 v152, v72
	v_exp_f32_e32 v153, v73
	v_exp_f32_e32 v154, v74
	v_exp_f32_e32 v155, v75
	v_add_f32_e32 v0, v148, v0
	v_add_f32_e32 v0, v149, v0
	v_add_f32_e32 v0, v150, v0
	v_add_f32_e32 v0, v151, v0
	s_waitcnt lgkmcnt(8)
	v_mfma_f32_32x32x16_bf16 v[128:143], v[44:47], v[84:87], v[128:143]
	v_exp_f32_e32 v156, v76
	v_exp_f32_e32 v157, v77
	v_exp_f32_e32 v158, v78
	v_exp_f32_e32 v159, v79
	v_add_f32_e32 v0, v152, v0
	v_add_f32_e32 v0, v153, v0
	v_add_f32_e32 v0, v154, v0
	v_add_f32_e32 v0, v155, v0
	v_cvt_pk_bf16_f32 v88, v144, v145
	v_cvt_pk_bf16_f32 v89, v146, v147
	v_cvt_pk_bf16_f32 v90, v148, v149
	v_cvt_pk_bf16_f32 v91, v150, v151
	v_add_f32_e32 v0, v156, v0
	v_add_f32_e32 v0, v157, v0
	v_add_f32_e32 v0, v158, v0
	v_add_f32_e32 v0, v159, v0
	v_cvt_pk_bf16_f32 v92, v152, v153
	v_cvt_pk_bf16_f32 v93, v154, v155
	v_cvt_pk_bf16_f32 v94, v156, v157
	v_cvt_pk_bf16_f32 v95, v158, v159
	v_add_f32_e32 v15, v253, v0
	s_waitcnt lgkmcnt(6)
	s_nop 0
	v_mfma_f32_32x32x16_bf16 v[96:111], v[48:51], v[88:91], v[96:111]
	s_waitcnt lgkmcnt(4)
	v_mfma_f32_32x32x16_bf16 v[128:143], v[52:55], v[88:91], v[128:143]
	s_waitcnt lgkmcnt(2)
	v_mfma_f32_32x32x16_bf16 v[96:111], v[56:59], v[92:95], v[96:111]
	s_waitcnt lgkmcnt(0)
	v_mfma_f32_32x32x16_bf16 v[128:143], v[60:63], v[92:95], v[128:143]
	v_mov_b32_e32 v253, v15
	s_branch .LBB0_1228
; DI unsigned pack2(float a, float b) { bf2_t v = __builtin_convertvector((f32x2){a, b}, bf2_t); return __builtin_bit_cast(unsigned, v); }
; #define MFMA32(a, b, c) __builtin_amdgcn_mfma_f32_32x32x16_bf16((a), (b), (c), 0, 0, 0)
; template <int DQK, int MODE, bool QN, bool KN> ...
;     ...
;       } else if (fixed_shift) {
;         float ps = 0.f;
; #pragma unroll
;         for (int kb = 0; kb < 2; ++kb)
; #pragma unroll
;           for (int i = 0; i < 16; ++i) { const float pv = __builtin_amdgcn_exp2f(sacc[kb][i]); sacc[kb][i] = pv; ps += pv; }
;         l_run += ps;
;     ...
; #pragma unroll
;       for (int kb = 0; kb < 2; ++kb)
; #pragma unroll
;         for (int s2 = 0; s2 < 2; ++s2) {
;           u32x4 pw;
;           pw.x = pack2(sacc[kb][8 * s2 + 0], sacc[kb][8 * s2 + 1]); pw.y = pack2(sacc[kb][8 * s2 + 2], sacc[kb][8 * s2 + 3]);
;           pw.z = pack2(sacc[kb][8 * s2 + 4], sacc[kb][8 * s2 + 5]); pw.w = pack2(sacc[kb][8 * s2 + 6], sacc[kb][8 * s2 + 7]);
;           const bf16x8 pf = __builtin_bit_cast(bf16x8, pw);
; #pragma unroll
;           for (int dvb = 0; dvb < 2; ++dvb) {
;             const char* vb = sV + dvb * VIMG + (kb * 32 + 16 * s2) * 64 + vtr_off;
;             const s16x4 v0 = tr_read(vb), v1 = tr_read(vb + 8 * 64);
;             const bf16x8 vf = __builtin_shufflevector(v0, v1, 0, 1, 2, 3, 4, 5, 6, 7);
;             o[dvb] = MFMA32(vf, pf, o[dvb]);
;           }
;         }
.Lmfp_3:
	s_waitcnt lgkmcnt(5)
	v_mfma_f32_32x32x16_bf16 v[64:79], v[112:115], v[160:163], v[16:31]
	s_waitcnt lgkmcnt(4)
	v_mfma_f32_32x32x16_bf16 v[64:79], v[116:119], v[164:167], v[64:79]
	s_nop 7
	v_exp_f32_e32 v112, v80
	v_exp_f32_e32 v113, v81
	v_exp_f32_e32 v114, v82
	v_exp_f32_e32 v115, v83
	v_add_u32_e32 v14, 0x11110, v249
	s_waitcnt lgkmcnt(3)
	v_mfma_f32_32x32x16_bf16 v[64:79], v[120:123], v[168:171], v[64:79]
	v_exp_f32_e32 v116, v84
	v_exp_f32_e32 v117, v85
	v_exp_f32_e32 v118, v86
	v_exp_f32_e32 v119, v87
	v_add_f32_e32 v0, 0, v112
	v_add_f32_e32 v0, v113, v0
	v_add_f32_e32 v0, v114, v0
	v_add_f32_e32 v0, v115, v0
	s_waitcnt lgkmcnt(2)
	v_mfma_f32_32x32x16_bf16 v[64:79], v[124:127], v[172:175], v[64:79]
	v_exp_f32_e32 v120, v88
	v_exp_f32_e32 v121, v89
	v_exp_f32_e32 v122, v90
	v_exp_f32_e32 v123, v91
	v_add_f32_e32 v0, v116, v0
	v_add_f32_e32 v0, v117, v0
	v_add_f32_e32 v0, v118, v0
	v_add_f32_e32 v0, v119, v0
	s_waitcnt lgkmcnt(1)
	v_mfma_f32_32x32x16_bf16 v[64:79], v[144:147], v[176:179], v[64:79]
	v_exp_f32_e32 v124, v92
	v_exp_f32_e32 v125, v93
	v_exp_f32_e32 v126, v94
	v_exp_f32_e32 v127, v95
	v_add_f32_e32 v0, v120, v0
	v_add_f32_e32 v0, v121, v0
	v_add_f32_e32 v0, v122, v0
	v_add_f32_e32 v0, v123, v0
	s_waitcnt lgkmcnt(0)
	v_mfma_f32_32x32x16_bf16 v[64:79], v[148:151], v[180:183], v[64:79]
	ds_read_b64_tr_b16 v[32:33], v14 offset:4096
	ds_read_b64_tr_b16 v[34:35], v14 offset:4608
	ds_read_b64_tr_b16 v[36:37], v14 offset:12288
	ds_read_b64_tr_b16 v[38:39], v14 offset:12800
	ds_read_b64_tr_b16 v[40:41], v14 offset:5120
	ds_read_b64_tr_b16 v[42:43], v14 offset:5632
	ds_read_b64_tr_b16 v[44:45], v14 offset:13312
	ds_read_b64_tr_b16 v[46:47], v14 offset:13824
	ds_read_b64_tr_b16 v[48:49], v14 offset:6144
	ds_read_b64_tr_b16 v[50:51], v14 offset:6656
	ds_read_b64_tr_b16 v[52:53], v14 offset:14336
	ds_read_b64_tr_b16 v[54:55], v14 offset:14848
	v_add_f32_e32 v0, v124, v0
	v_add_f32_e32 v0, v125, v0
	v_add_f32_e32 v0, v126, v0
	v_add_f32_e32 v0, v127, v0
	v_cvt_pk_bf16_f32 v80, v112, v113
	v_cvt_pk_bf16_f32 v81, v114, v115
	v_cvt_pk_bf16_f32 v82, v116, v117
	v_cvt_pk_bf16_f32 v83, v118, v119
	v_cvt_pk_bf16_f32 v84, v120, v121
	v_cvt_pk_bf16_f32 v85, v122, v123
	v_cvt_pk_bf16_f32 v86, v124, v125
	v_cvt_pk_bf16_f32 v87, v126, v127
	s_waitcnt lgkmcnt(10)
	s_nop 0
	v_mfma_f32_32x32x16_bf16 v[96:111], v[32:35], v[80:83], v[96:111]
	v_exp_f32_e32 v144, v64
	v_exp_f32_e32 v145, v65
	v_exp_f32_e32 v146, v66
	v_exp_f32_e32 v147, v67
	s_waitcnt lgkmcnt(8)
	v_mfma_f32_32x32x16_bf16 v[128:143], v[36:39], v[80:83], v[128:143]
	ds_read_b64_tr_b16 v[56:57], v14 offset:7168
	ds_read_b64_tr_b16 v[58:59], v14 offset:7680
	ds_read_b64_tr_b16 v[60:61], v14 offset:15360
	ds_read_b64_tr_b16 v[62:63], v14 offset:15872
	v_exp_f32_e32 v148, v68
	v_exp_f32_e32 v149, v69
	v_exp_f32_e32 v150, v70
	v_exp_f32_e32 v151, v71
	v_add_f32_e32 v0, v144, v0
	v_add_f32_e32 v0, v145, v0
	v_add_f32_e32 v0, v146, v0
	v_add_f32_e32 v0, v147, v0
	s_waitcnt lgkmcnt(10)
	v_mfma_f32_32x32x16_bf16 v[96:111], v[40:43], v[84:87], v[96:111]
	v_exp_f32_e32 v152, v72
	v_exp_f32_e32 v153, v73
	v_exp_f32_e32 v154, v74
	v_exp_f32_e32 v155, v75
	v_add_f32_e32 v0, v148, v0
	v_add_f32_e32 v0, v149, v0
	v_add_f32_e32 v0, v150, v0
	v_add_f32_e32 v0, v151, v0
	s_waitcnt lgkmcnt(8)
	v_mfma_f32_32x32x16_bf16 v[128:143], v[44:47], v[84:87], v[128:143]
	v_exp_f32_e32 v156, v76
	v_exp_f32_e32 v157, v77
	v_exp_f32_e32 v158, v78
	v_exp_f32_e32 v159, v79
	v_add_f32_e32 v0, v152, v0
	v_add_f32_e32 v0, v153, v0
	v_add_f32_e32 v0, v154, v0
	v_add_f32_e32 v0, v155, v0
	v_cvt_pk_bf16_f32 v88, v144, v145
	v_cvt_pk_bf16_f32 v89, v146, v147
	v_cvt_pk_bf16_f32 v90, v148, v149
	v_cvt_pk_bf16_f32 v91, v150, v151
	v_add_f32_e32 v0, v156, v0
	v_add_f32_e32 v0, v157, v0
	v_add_f32_e32 v0, v158, v0
	v_add_f32_e32 v0, v159, v0
	v_cvt_pk_bf16_f32 v92, v152, v153
	v_cvt_pk_bf16_f32 v93, v154, v155
	v_cvt_pk_bf16_f32 v94, v156, v157
	v_cvt_pk_bf16_f32 v95, v158, v159
	v_add_f32_e32 v15, v253, v0
	s_waitcnt lgkmcnt(6)
	s_nop 0
	v_mfma_f32_32x32x16_bf16 v[96:111], v[48:51], v[88:91], v[96:111]
	s_waitcnt lgkmcnt(4)
	v_mfma_f32_32x32x16_bf16 v[128:143], v[52:55], v[88:91], v[128:143]
	s_waitcnt lgkmcnt(2)
	v_mfma_f32_32x32x16_bf16 v[96:111], v[56:59], v[92:95], v[96:111]
	s_waitcnt lgkmcnt(0)
	v_mfma_f32_32x32x16_bf16 v[128:143], v[60:63], v[92:95], v[128:143]
	v_mov_b32_e32 v253, v15
	s_branch .LBB0_1197
